# SwiGLU epilogue with two-groups-ahead ssq prefetch + MFMA accumulator clear
# baseline (speedup 1.0000x reference)
; __device__ __forceinline__ unsigned cvtpk(float lo, float hi) { f32x2_t v = {lo, hi}; bf16x2_t b = __builtin_convertvector(v, bf16x2_t); return __builtin_bit_cast(unsigned, b); }
; __device__ __forceinline__ float ssq_sum(const float* p) {
;     const f32x4 a = *(const f32x4*)p, b = *(const f32x4*)(p + 4), c = *(const f32x4*)(p + 8), d = *(const f32x4*)(p + 12);
;     return (((a[0] + a[1]) + (a[2] + a[3])) + ((b[0] + b[1]) + (b[2] + b[3]))) + (((c[0] + c[1]) + (c[2] + c[3])) + ((d[0] + d[1]) + (d[2] + d[3])));
;     __device__ __forceinline__ void operator()(const f32x4 (&acc)[2][2][4][2], const Unit& u, int wr, int wc, int fr, int fq) const {
;         const int row0 = u.pm * BM + wr * 64 + fr, col0 = u.pn * 128 + wc * 32 + 8 * fq;
; #pragma unroll
;         for (int ai = 0; ai < 2; ++ai)
; #pragma unroll
;             for (int m = 0; m < 4; ++m) {
;                 const int row = row0 + ai * HALF + m * 16;
;                 const float rs = 1.0f / sqrtf(ssq_sum(ssq + (size_t)row * 16) * (1.0f / DM) + EPS);
;                 float hv[8];
; #pragma unroll
;                 for (int n = 0; n < 2; ++n)
; #pragma unroll
;                     for (int e = 0; e < 4; ++e) {
;                         const float gg = acc[ai][0][m][n][e] * rs, uu = acc[ai][1][m][n][e] * rs;
;                         const float den = 1.0f + __builtin_amdgcn_exp2f(-gg * LOG2E);
;                         hv[n * 4 + e] = gg * uu * __builtin_amdgcn_rcpf(den);
;                     }
;                 u32x4 w; w.x = cvtpk(hv[0], hv[1]); w.y = cvtpk(hv[2], hv[3]); w.z = cvtpk(hv[4], hv[5]); w.w = cvtpk(hv[6], hv[7]);
;                 *(u32x4*)(H + (size_t)row * DFF + col0) = w;
;             }
.LBB0_244:
	v_lshl_add_u32 v148, s8, 8, v152
	v_ashrrev_i32_e32 v149, 31, v148
	v_lshlrev_b64 v[144:145], 6, v[148:149]
	v_lshl_add_u64 v[144:145], s[14:15], 0, v[144:145]
	global_load_dwordx4 v[160:163], v[144:145], off
	global_load_dwordx4 v[164:167], v[144:145], off offset:16
	global_load_dwordx4 v[168:171], v[144:145], off offset:32
	global_load_dwordx4 v[172:175], v[144:145], off offset:48
	v_mov_b64_e32 v[146:147], s[16:17]
	v_mad_i64_i32 v[176:177], s[8:9], v148, s56, v[146:147]
	v_lshl_or_b32 v150, s2, 7, v154
	v_mov_b32_e32 v151, 0
	v_lshlrev_b64 v[150:151], 1, v[150:151]
	v_lshl_add_u64 v[176:177], v[176:177], 0, v[150:151]
	s_mov_b32 s8, 0x2000
	s_mov_b32 s9, 0
	v_lshl_add_u64 v[146:147], v[144:145], 0, s[8:9]
	global_load_dwordx4 v[180:183], v[144:145], off offset:1024
	global_load_dwordx4 v[184:187], v[144:145], off offset:1040
	global_load_dwordx4 v[188:191], v[144:145], off offset:1056
	global_load_dwordx4 v[192:195], v[144:145], off offset:1072
	s_waitcnt vmcnt(4)
	v_pk_add_f32 v[160:161], v[160:161], v[162:163]
	v_pk_add_f32 v[164:165], v[164:165], v[166:167]
	v_pk_add_f32 v[168:169], v[168:169], v[170:171]
	v_pk_add_f32 v[172:173], v[172:173], v[174:175]
	v_pk_add_f32 v[160:161], v[160:161], v[164:165]
	v_pk_add_f32 v[168:169], v[168:169], v[172:173]
	v_pk_add_f32 v[160:161], v[160:161], v[168:169]
	v_add_f32_e32 v149, v160, v161
	v_fmamk_f32 v149, v149, 0x3a800000, v158
	v_rsq_f32_e32 v150, v149
	global_load_dwordx4 v[196:199], v[144:145], off offset:2048
	global_load_dwordx4 v[200:203], v[144:145], off offset:2064
	global_load_dwordx4 v[204:207], v[144:145], off offset:2080
	global_load_dwordx4 v[208:211], v[144:145], off offset:2096
	v_pk_mul_f32 v[116:117], v[124:125], v[116:117]
	v_pk_mul_f32 v[118:119], v[126:127], v[118:119]
	v_pk_mul_f32 v[112:113], v[120:121], v[112:113]
	v_pk_mul_f32 v[114:115], v[122:123], v[114:115]
	v_mul_f32_e32 v150, 0xbfb8aa3b, v150
	v_mov_b32_e32 v151, v149
	v_pk_mul_f32 v[124:125], v[124:125], v[150:151] op_sel_hi:[1,0]
	v_pk_mul_f32 v[126:127], v[126:127], v[150:151] op_sel_hi:[1,0]
	v_pk_mul_f32 v[120:121], v[120:121], v[150:151] op_sel_hi:[1,0]
	v_pk_mul_f32 v[122:123], v[122:123], v[150:151] op_sel_hi:[1,0]
	v_exp_f32_e32 v124, v124
	v_exp_f32_e32 v125, v125
	v_exp_f32_e32 v126, v126
	v_exp_f32_e32 v127, v127
	v_exp_f32_e32 v120, v120
	v_exp_f32_e32 v121, v121
	v_exp_f32_e32 v122, v122
	v_exp_f32_e32 v123, v123
	v_fma_f32 v124, v124, v149, v149
	v_fma_f32 v125, v125, v149, v149
	v_fma_f32 v126, v126, v149, v149
	v_fma_f32 v127, v127, v149, v149
	v_fma_f32 v120, v120, v149, v149
	v_fma_f32 v121, v121, v149, v149
	v_fma_f32 v122, v122, v149, v149
	v_fma_f32 v123, v123, v149, v149
	v_rcp_f32_e32 v124, v124
	v_rcp_f32_e32 v125, v125
	v_rcp_f32_e32 v126, v126
	v_rcp_f32_e32 v127, v127
	v_rcp_f32_e32 v120, v120
	v_rcp_f32_e32 v121, v121
	v_rcp_f32_e32 v122, v122
	v_rcp_f32_e32 v123, v123
	v_pk_mul_f32 v[116:117], v[116:117], v[124:125]
	v_pk_mul_f32 v[118:119], v[118:119], v[126:127]
	v_pk_mul_f32 v[112:113], v[112:113], v[120:121]
	v_pk_mul_f32 v[114:115], v[114:115], v[122:123]
	v_cvt_pk_bf16_f32 v124, v116, v117
	v_cvt_pk_bf16_f32 v125, v118, v119
	v_cvt_pk_bf16_f32 v126, v112, v113
	v_cvt_pk_bf16_f32 v127, v114, v115
	global_store_dwordx4 v[176:177], v[124:127], off
	s_waitcnt vmcnt(5)
	v_pk_add_f32 v[180:181], v[180:181], v[182:183]
	v_pk_add_f32 v[184:185], v[184:185], v[186:187]
	v_pk_add_f32 v[188:189], v[188:189], v[190:191]
	v_pk_add_f32 v[192:193], v[192:193], v[194:195]
	v_pk_add_f32 v[180:181], v[180:181], v[184:185]
	v_pk_add_f32 v[188:189], v[188:189], v[192:193]
	v_pk_add_f32 v[180:181], v[180:181], v[188:189]
	v_add_f32_e32 v149, v180, v181
	v_fmamk_f32 v149, v149, 0x3a800000, v158
	v_rsq_f32_e32 v150, v149
	global_load_dwordx4 v[160:163], v[144:145], off offset:3072
	global_load_dwordx4 v[164:167], v[144:145], off offset:3088
	global_load_dwordx4 v[168:171], v[144:145], off offset:3104
	global_load_dwordx4 v[172:175], v[144:145], off offset:3120
	v_pk_mul_f32 v[100:101], v[108:109], v[100:101]
	v_pk_mul_f32 v[102:103], v[110:111], v[102:103]
	v_pk_mul_f32 v[96:97], v[104:105], v[96:97]
	v_pk_mul_f32 v[98:99], v[106:107], v[98:99]
	v_mul_f32_e32 v150, 0xbfb8aa3b, v150
	v_mov_b32_e32 v151, v149
	v_pk_mul_f32 v[108:109], v[108:109], v[150:151] op_sel_hi:[1,0]
	v_pk_mul_f32 v[110:111], v[110:111], v[150:151] op_sel_hi:[1,0]
	v_pk_mul_f32 v[104:105], v[104:105], v[150:151] op_sel_hi:[1,0]
	v_pk_mul_f32 v[106:107], v[106:107], v[150:151] op_sel_hi:[1,0]
	v_exp_f32_e32 v108, v108
	v_exp_f32_e32 v109, v109
	v_exp_f32_e32 v110, v110
	v_exp_f32_e32 v111, v111
	v_exp_f32_e32 v104, v104
	v_exp_f32_e32 v105, v105
	v_exp_f32_e32 v106, v106
	v_exp_f32_e32 v107, v107
	v_fma_f32 v108, v108, v149, v149
	v_fma_f32 v109, v109, v149, v149
	v_fma_f32 v110, v110, v149, v149
	v_fma_f32 v111, v111, v149, v149
	v_fma_f32 v104, v104, v149, v149
	v_fma_f32 v105, v105, v149, v149
	v_fma_f32 v106, v106, v149, v149
	v_fma_f32 v107, v107, v149, v149
	v_rcp_f32_e32 v108, v108
	v_rcp_f32_e32 v109, v109
	v_rcp_f32_e32 v110, v110
	v_rcp_f32_e32 v111, v111
	v_rcp_f32_e32 v104, v104
	v_rcp_f32_e32 v105, v105
	v_rcp_f32_e32 v106, v106
	v_rcp_f32_e32 v107, v107
	s_mov_b32 s8, 0x16000
	v_pk_mul_f32 v[100:101], v[100:101], v[108:109]
	v_pk_mul_f32 v[102:103], v[102:103], v[110:111]
	v_pk_mul_f32 v[96:97], v[96:97], v[104:105]
	v_pk_mul_f32 v[98:99], v[98:99], v[106:107]
	v_cvt_pk_bf16_f32 v108, v100, v101
	v_cvt_pk_bf16_f32 v109, v102, v103
	v_cvt_pk_bf16_f32 v110, v96, v97
	v_cvt_pk_bf16_f32 v111, v98, v99
	v_lshl_add_u64 v[178:179], v[176:177], 0, s[8:9]
	global_store_dwordx4 v[178:179], v[108:111], off
	s_waitcnt vmcnt(6)
; __device__ __forceinline__ unsigned cvtpk(float lo, float hi) { f32x2_t v = {lo, hi}; bf16x2_t b = __builtin_convertvector(v, bf16x2_t); return __builtin_bit_cast(unsigned, b); }
; __device__ __forceinline__ float ssq_sum(const float* p) {
;     const f32x4 a = *(const f32x4*)p, b = *(const f32x4*)(p + 4), c = *(const f32x4*)(p + 8), d = *(const f32x4*)(p + 12);
;     return (((a[0] + a[1]) + (a[2] + a[3])) + ((b[0] + b[1]) + (b[2] + b[3]))) + (((c[0] + c[1]) + (c[2] + c[3])) + ((d[0] + d[1]) + (d[2] + d[3])));
;     __device__ __forceinline__ void operator()(const f32x4 (&acc)[2][2][4][2], const Unit& u, int wr, int wc, int fr, int fq) const {
;         const int row0 = u.pm * BM + wr * 64 + fr, col0 = u.pn * 128 + wc * 32 + 8 * fq;
; #pragma unroll
;         for (int ai = 0; ai < 2; ++ai)
; #pragma unroll
;             for (int m = 0; m < 4; ++m) {
;                 const int row = row0 + ai * HALF + m * 16;
;                 const float rs = 1.0f / sqrtf(ssq_sum(ssq + (size_t)row * 16) * (1.0f / DM) + EPS);
;                 float hv[8];
; #pragma unroll
;                 for (int n = 0; n < 2; ++n)
; #pragma unroll
;                     for (int e = 0; e < 4; ++e) {
;                         const float gg = acc[ai][0][m][n][e] * rs, uu = acc[ai][1][m][n][e] * rs;
;                         const float den = 1.0f + __builtin_amdgcn_exp2f(-gg * LOG2E);
;                         hv[n * 4 + e] = gg * uu * __builtin_amdgcn_rcpf(den);
;                     }
;                 u32x4 w; w.x = cvtpk(hv[0], hv[1]); w.y = cvtpk(hv[2], hv[3]); w.z = cvtpk(hv[4], hv[5]); w.w = cvtpk(hv[6], hv[7]);
;                 *(u32x4*)(H + (size_t)row * DFF + col0) = w;
;             }
	v_pk_add_f32 v[196:197], v[196:197], v[198:199]
	v_pk_add_f32 v[200:201], v[200:201], v[202:203]
	v_pk_add_f32 v[204:205], v[204:205], v[206:207]
	v_pk_add_f32 v[208:209], v[208:209], v[210:211]
	v_pk_add_f32 v[196:197], v[196:197], v[200:201]
	v_pk_add_f32 v[204:205], v[204:205], v[208:209]
	v_pk_add_f32 v[196:197], v[196:197], v[204:205]
	v_add_f32_e32 v149, v196, v197
	v_fmamk_f32 v149, v149, 0x3a800000, v158
	v_rsq_f32_e32 v150, v149
	global_load_dwordx4 v[180:183], v[146:147], off
	global_load_dwordx4 v[184:187], v[146:147], off offset:16
	global_load_dwordx4 v[188:191], v[146:147], off offset:32
	global_load_dwordx4 v[192:195], v[146:147], off offset:48
	v_pk_mul_f32 v[84:85], v[92:93], v[84:85]
	v_pk_mul_f32 v[86:87], v[94:95], v[86:87]
	v_pk_mul_f32 v[80:81], v[88:89], v[80:81]
	v_pk_mul_f32 v[82:83], v[90:91], v[82:83]
	v_mul_f32_e32 v150, 0xbfb8aa3b, v150
	v_mov_b32_e32 v151, v149
	v_pk_mul_f32 v[92:93], v[92:93], v[150:151] op_sel_hi:[1,0]
	v_pk_mul_f32 v[94:95], v[94:95], v[150:151] op_sel_hi:[1,0]
	v_pk_mul_f32 v[88:89], v[88:89], v[150:151] op_sel_hi:[1,0]
	v_pk_mul_f32 v[90:91], v[90:91], v[150:151] op_sel_hi:[1,0]
	v_exp_f32_e32 v92, v92
	v_exp_f32_e32 v93, v93
	v_exp_f32_e32 v94, v94
	v_exp_f32_e32 v95, v95
	v_exp_f32_e32 v88, v88
	v_exp_f32_e32 v89, v89
	v_exp_f32_e32 v90, v90
	v_exp_f32_e32 v91, v91
	v_fma_f32 v92, v92, v149, v149
	v_fma_f32 v93, v93, v149, v149
	v_fma_f32 v94, v94, v149, v149
	v_fma_f32 v95, v95, v149, v149
	v_fma_f32 v88, v88, v149, v149
	v_fma_f32 v89, v89, v149, v149
	v_fma_f32 v90, v90, v149, v149
	v_fma_f32 v91, v91, v149, v149
	v_rcp_f32_e32 v92, v92
	v_rcp_f32_e32 v93, v93
	v_rcp_f32_e32 v94, v94
	v_rcp_f32_e32 v95, v95
	v_rcp_f32_e32 v88, v88
	v_rcp_f32_e32 v89, v89
	v_rcp_f32_e32 v90, v90
	v_rcp_f32_e32 v91, v91
	s_mov_b32 s8, 0x2c000
	v_pk_mul_f32 v[84:85], v[84:85], v[92:93]
	v_pk_mul_f32 v[86:87], v[86:87], v[94:95]
	v_pk_mul_f32 v[80:81], v[80:81], v[88:89]
	v_pk_mul_f32 v[82:83], v[82:83], v[90:91]
	v_cvt_pk_bf16_f32 v92, v84, v85
	v_cvt_pk_bf16_f32 v93, v86, v87
	v_cvt_pk_bf16_f32 v94, v80, v81
	v_cvt_pk_bf16_f32 v95, v82, v83
	v_lshl_add_u64 v[178:179], v[176:177], 0, s[8:9]
	global_store_dwordx4 v[178:179], v[92:95], off
	s_waitcnt vmcnt(6)
	v_pk_add_f32 v[160:161], v[160:161], v[162:163]
	v_pk_add_f32 v[164:165], v[164:165], v[166:167]
	v_pk_add_f32 v[168:169], v[168:169], v[170:171]
	v_pk_add_f32 v[172:173], v[172:173], v[174:175]
	v_pk_add_f32 v[160:161], v[160:161], v[164:165]
	v_pk_add_f32 v[168:169], v[168:169], v[172:173]
	v_pk_add_f32 v[160:161], v[160:161], v[168:169]
	v_add_f32_e32 v149, v160, v161
	v_fmamk_f32 v149, v149, 0x3a800000, v158
	v_rsq_f32_e32 v150, v149
	global_load_dwordx4 v[196:199], v[146:147], off offset:1024
	global_load_dwordx4 v[200:203], v[146:147], off offset:1040
	global_load_dwordx4 v[204:207], v[146:147], off offset:1056
	global_load_dwordx4 v[208:211], v[146:147], off offset:1072
	v_pk_mul_f32 v[68:69], v[76:77], v[68:69]
	v_pk_mul_f32 v[70:71], v[78:79], v[70:71]
	v_pk_mul_f32 v[64:65], v[72:73], v[64:65]
	v_pk_mul_f32 v[66:67], v[74:75], v[66:67]
	v_mul_f32_e32 v150, 0xbfb8aa3b, v150
	v_mov_b32_e32 v151, v149
	v_pk_mul_f32 v[76:77], v[76:77], v[150:151] op_sel_hi:[1,0]
	v_pk_mul_f32 v[78:79], v[78:79], v[150:151] op_sel_hi:[1,0]
	v_pk_mul_f32 v[72:73], v[72:73], v[150:151] op_sel_hi:[1,0]
	v_pk_mul_f32 v[74:75], v[74:75], v[150:151] op_sel_hi:[1,0]
	v_exp_f32_e32 v76, v76
	v_exp_f32_e32 v77, v77
	v_exp_f32_e32 v78, v78
	v_exp_f32_e32 v79, v79
	v_exp_f32_e32 v72, v72
	v_exp_f32_e32 v73, v73
	v_exp_f32_e32 v74, v74
	v_exp_f32_e32 v75, v75
	v_fma_f32 v76, v76, v149, v149
	v_fma_f32 v77, v77, v149, v149
	v_fma_f32 v78, v78, v149, v149
	v_fma_f32 v79, v79, v149, v149
	v_fma_f32 v72, v72, v149, v149
	v_fma_f32 v73, v73, v149, v149
	v_fma_f32 v74, v74, v149, v149
	v_fma_f32 v75, v75, v149, v149
	v_rcp_f32_e32 v76, v76
	v_rcp_f32_e32 v77, v77
	v_rcp_f32_e32 v78, v78
	v_rcp_f32_e32 v79, v79
	v_rcp_f32_e32 v72, v72
	v_rcp_f32_e32 v73, v73
	v_rcp_f32_e32 v74, v74
	v_rcp_f32_e32 v75, v75
	s_mov_b32 s8, 0x42000
	v_pk_mul_f32 v[68:69], v[68:69], v[76:77]
	v_pk_mul_f32 v[70:71], v[70:71], v[78:79]
	v_pk_mul_f32 v[64:65], v[64:65], v[72:73]
	v_pk_mul_f32 v[66:67], v[66:67], v[74:75]
	v_cvt_pk_bf16_f32 v76, v68, v69
	v_cvt_pk_bf16_f32 v77, v70, v71
	v_cvt_pk_bf16_f32 v78, v64, v65
	v_cvt_pk_bf16_f32 v79, v66, v67
	v_lshl_add_u64 v[178:179], v[176:177], 0, s[8:9]
	global_store_dwordx4 v[178:179], v[76:79], off
	s_waitcnt vmcnt(6)
	v_pk_add_f32 v[180:181], v[180:181], v[182:183]
	v_pk_add_f32 v[184:185], v[184:185], v[186:187]
	v_pk_add_f32 v[188:189], v[188:189], v[190:191]
	v_pk_add_f32 v[192:193], v[192:193], v[194:195]
	v_pk_add_f32 v[180:181], v[180:181], v[184:185]
	v_pk_add_f32 v[188:189], v[188:189], v[192:193]
	v_pk_add_f32 v[180:181], v[180:181], v[188:189]
	v_add_f32_e32 v149, v180, v181
	v_fmamk_f32 v149, v149, 0x3a800000, v158
	v_rsq_f32_e32 v150, v149
	global_load_dwordx4 v[160:163], v[146:147], off offset:2048
	global_load_dwordx4 v[164:167], v[146:147], off offset:2064
	global_load_dwordx4 v[168:171], v[146:147], off offset:2080
	global_load_dwordx4 v[172:175], v[146:147], off offset:2096
	v_pk_mul_f32 v[52:53], v[60:61], v[52:53]
	v_pk_mul_f32 v[54:55], v[62:63], v[54:55]
	v_pk_mul_f32 v[48:49], v[56:57], v[48:49]
	v_pk_mul_f32 v[50:51], v[58:59], v[50:51]
	v_mul_f32_e32 v150, 0xbfb8aa3b, v150
	v_mov_b32_e32 v151, v149
	v_pk_mul_f32 v[60:61], v[60:61], v[150:151] op_sel_hi:[1,0]
	v_pk_mul_f32 v[62:63], v[62:63], v[150:151] op_sel_hi:[1,0]
	v_pk_mul_f32 v[56:57], v[56:57], v[150:151] op_sel_hi:[1,0]
	v_pk_mul_f32 v[58:59], v[58:59], v[150:151] op_sel_hi:[1,0]
	v_exp_f32_e32 v60, v60
	v_exp_f32_e32 v61, v61
	v_exp_f32_e32 v62, v62
	v_exp_f32_e32 v63, v63
	v_exp_f32_e32 v56, v56
	v_exp_f32_e32 v57, v57
	v_exp_f32_e32 v58, v58
	v_exp_f32_e32 v59, v59
	v_fma_f32 v60, v60, v149, v149
	v_fma_f32 v61, v61, v149, v149
	v_fma_f32 v62, v62, v149, v149
	v_fma_f32 v63, v63, v149, v149
	v_fma_f32 v56, v56, v149, v149
	v_fma_f32 v57, v57, v149, v149
	v_fma_f32 v58, v58, v149, v149
	v_fma_f32 v59, v59, v149, v149
	v_rcp_f32_e32 v60, v60
	v_rcp_f32_e32 v61, v61
	v_rcp_f32_e32 v62, v62
	v_rcp_f32_e32 v63, v63
	v_rcp_f32_e32 v56, v56
	v_rcp_f32_e32 v57, v57
	v_rcp_f32_e32 v58, v58
	v_rcp_f32_e32 v59, v59
	s_mov_b32 s8, 0xb0000
	v_pk_mul_f32 v[52:53], v[52:53], v[60:61]
	v_pk_mul_f32 v[54:55], v[54:55], v[62:63]
	v_pk_mul_f32 v[48:49], v[48:49], v[56:57]
	v_pk_mul_f32 v[50:51], v[50:51], v[58:59]
	v_cvt_pk_bf16_f32 v60, v52, v53
	v_cvt_pk_bf16_f32 v61, v54, v55
	v_cvt_pk_bf16_f32 v62, v48, v49
	v_cvt_pk_bf16_f32 v63, v50, v51
	v_lshl_add_u64 v[178:179], v[176:177], 0, s[8:9]
	global_store_dwordx4 v[178:179], v[60:63], off
	s_waitcnt vmcnt(6)
; __device__ __forceinline__ unsigned cvtpk(float lo, float hi) { f32x2_t v = {lo, hi}; bf16x2_t b = __builtin_convertvector(v, bf16x2_t); return __builtin_bit_cast(unsigned, b); }
; __device__ __forceinline__ float ssq_sum(const float* p) {
;     const f32x4 a = *(const f32x4*)p, b = *(const f32x4*)(p + 4), c = *(const f32x4*)(p + 8), d = *(const f32x4*)(p + 12);
;     return (((a[0] + a[1]) + (a[2] + a[3])) + ((b[0] + b[1]) + (b[2] + b[3]))) + (((c[0] + c[1]) + (c[2] + c[3])) + ((d[0] + d[1]) + (d[2] + d[3])));
;     __device__ __forceinline__ void operator()(const f32x4 (&acc)[2][2][4][2], const Unit& u, int wr, int wc, int fr, int fq) const {
;         const int row0 = u.pm * BM + wr * 64 + fr, col0 = u.pn * 128 + wc * 32 + 8 * fq;
; #pragma unroll
;         for (int ai = 0; ai < 2; ++ai)
; #pragma unroll
;             for (int m = 0; m < 4; ++m) {
;                 const int row = row0 + ai * HALF + m * 16;
;                 const float rs = 1.0f / sqrtf(ssq_sum(ssq + (size_t)row * 16) * (1.0f / DM) + EPS);
;                 float hv[8];
; #pragma unroll
;                 for (int n = 0; n < 2; ++n)
; #pragma unroll
;                     for (int e = 0; e < 4; ++e) {
;                         const float gg = acc[ai][0][m][n][e] * rs, uu = acc[ai][1][m][n][e] * rs;
;                         const float den = 1.0f + __builtin_amdgcn_exp2f(-gg * LOG2E);
;                         hv[n * 4 + e] = gg * uu * __builtin_amdgcn_rcpf(den);
;                     }
;                 u32x4 w; w.x = cvtpk(hv[0], hv[1]); w.y = cvtpk(hv[2], hv[3]); w.z = cvtpk(hv[4], hv[5]); w.w = cvtpk(hv[6], hv[7]);
;                 *(u32x4*)(H + (size_t)row * DFF + col0) = w;
;             }
	v_pk_add_f32 v[196:197], v[196:197], v[198:199]
	v_pk_add_f32 v[200:201], v[200:201], v[202:203]
	v_pk_add_f32 v[204:205], v[204:205], v[206:207]
	v_pk_add_f32 v[208:209], v[208:209], v[210:211]
	v_pk_add_f32 v[196:197], v[196:197], v[200:201]
	v_pk_add_f32 v[204:205], v[204:205], v[208:209]
	v_pk_add_f32 v[196:197], v[196:197], v[204:205]
	v_add_f32_e32 v149, v196, v197
	v_fmamk_f32 v149, v149, 0x3a800000, v158
	v_rsq_f32_e32 v150, v149
	global_load_dwordx4 v[180:183], v[146:147], off offset:3072
	global_load_dwordx4 v[184:187], v[146:147], off offset:3088
	global_load_dwordx4 v[188:191], v[146:147], off offset:3104
	global_load_dwordx4 v[192:195], v[146:147], off offset:3120
	v_pk_mul_f32 v[36:37], v[44:45], v[36:37]
	v_pk_mul_f32 v[38:39], v[46:47], v[38:39]
	v_pk_mul_f32 v[32:33], v[40:41], v[32:33]
	v_pk_mul_f32 v[34:35], v[42:43], v[34:35]
	v_mul_f32_e32 v150, 0xbfb8aa3b, v150
	v_mov_b32_e32 v151, v149
	v_pk_mul_f32 v[44:45], v[44:45], v[150:151] op_sel_hi:[1,0]
	v_pk_mul_f32 v[46:47], v[46:47], v[150:151] op_sel_hi:[1,0]
	v_pk_mul_f32 v[40:41], v[40:41], v[150:151] op_sel_hi:[1,0]
	v_pk_mul_f32 v[42:43], v[42:43], v[150:151] op_sel_hi:[1,0]
	v_exp_f32_e32 v44, v44
	v_exp_f32_e32 v45, v45
	v_exp_f32_e32 v46, v46
	v_exp_f32_e32 v47, v47
	v_exp_f32_e32 v40, v40
	v_exp_f32_e32 v41, v41
	v_exp_f32_e32 v42, v42
	v_exp_f32_e32 v43, v43
	v_fma_f32 v44, v44, v149, v149
	v_fma_f32 v45, v45, v149, v149
	v_fma_f32 v46, v46, v149, v149
	v_fma_f32 v47, v47, v149, v149
	v_fma_f32 v40, v40, v149, v149
	v_fma_f32 v41, v41, v149, v149
	v_fma_f32 v42, v42, v149, v149
	v_fma_f32 v43, v43, v149, v149
	v_rcp_f32_e32 v44, v44
	v_rcp_f32_e32 v45, v45
	v_rcp_f32_e32 v46, v46
	v_rcp_f32_e32 v47, v47
	v_rcp_f32_e32 v40, v40
	v_rcp_f32_e32 v41, v41
	v_rcp_f32_e32 v42, v42
	v_rcp_f32_e32 v43, v43
	s_mov_b32 s8, 0xc6000
	v_pk_mul_f32 v[36:37], v[36:37], v[44:45]
	v_pk_mul_f32 v[38:39], v[38:39], v[46:47]
	v_pk_mul_f32 v[32:33], v[32:33], v[40:41]
	v_pk_mul_f32 v[34:35], v[34:35], v[42:43]
	v_cvt_pk_bf16_f32 v44, v36, v37
	v_cvt_pk_bf16_f32 v45, v38, v39
	v_cvt_pk_bf16_f32 v46, v32, v33
	v_cvt_pk_bf16_f32 v47, v34, v35
	v_lshl_add_u64 v[178:179], v[176:177], 0, s[8:9]
	global_store_dwordx4 v[178:179], v[44:47], off
	s_waitcnt vmcnt(6)
	v_pk_add_f32 v[160:161], v[160:161], v[162:163]
	v_pk_add_f32 v[164:165], v[164:165], v[166:167]
	v_pk_add_f32 v[168:169], v[168:169], v[170:171]
	v_pk_add_f32 v[172:173], v[172:173], v[174:175]
	v_pk_add_f32 v[160:161], v[160:161], v[164:165]
	v_pk_add_f32 v[168:169], v[168:169], v[172:173]
	v_pk_add_f32 v[160:161], v[160:161], v[168:169]
	v_add_f32_e32 v149, v160, v161
	v_fmamk_f32 v149, v149, 0x3a800000, v158
	v_rsq_f32_e32 v150, v149
	v_pk_mul_f32 v[20:21], v[28:29], v[20:21]
	v_pk_mul_f32 v[22:23], v[30:31], v[22:23]
	v_pk_mul_f32 v[16:17], v[24:25], v[16:17]
	v_pk_mul_f32 v[18:19], v[26:27], v[18:19]
	v_mul_f32_e32 v150, 0xbfb8aa3b, v150
	v_mov_b32_e32 v151, v149
	v_pk_mul_f32 v[28:29], v[28:29], v[150:151] op_sel_hi:[1,0]
	v_pk_mul_f32 v[30:31], v[30:31], v[150:151] op_sel_hi:[1,0]
	v_pk_mul_f32 v[24:25], v[24:25], v[150:151] op_sel_hi:[1,0]
	v_pk_mul_f32 v[26:27], v[26:27], v[150:151] op_sel_hi:[1,0]
	v_exp_f32_e32 v28, v28
	v_exp_f32_e32 v29, v29
	v_exp_f32_e32 v30, v30
	v_exp_f32_e32 v31, v31
	v_exp_f32_e32 v24, v24
	v_exp_f32_e32 v25, v25
	v_exp_f32_e32 v26, v26
	v_exp_f32_e32 v27, v27
	v_fma_f32 v28, v28, v149, v149
	v_fma_f32 v29, v29, v149, v149
	v_fma_f32 v30, v30, v149, v149
	v_fma_f32 v31, v31, v149, v149
	v_fma_f32 v24, v24, v149, v149
	v_fma_f32 v25, v25, v149, v149
	v_fma_f32 v26, v26, v149, v149
	v_fma_f32 v27, v27, v149, v149
	v_rcp_f32_e32 v28, v28
	v_rcp_f32_e32 v29, v29
	v_rcp_f32_e32 v30, v30
	v_rcp_f32_e32 v31, v31
	v_rcp_f32_e32 v24, v24
	v_rcp_f32_e32 v25, v25
	v_rcp_f32_e32 v26, v26
	v_rcp_f32_e32 v27, v27
	s_mov_b32 s8, 0xdc000
	v_pk_mul_f32 v[20:21], v[20:21], v[28:29]
	v_pk_mul_f32 v[22:23], v[22:23], v[30:31]
	v_pk_mul_f32 v[16:17], v[16:17], v[24:25]
	v_pk_mul_f32 v[18:19], v[18:19], v[26:27]
	v_cvt_pk_bf16_f32 v28, v20, v21
	v_cvt_pk_bf16_f32 v29, v22, v23
	v_cvt_pk_bf16_f32 v30, v16, v17
	v_cvt_pk_bf16_f32 v31, v18, v19
	v_lshl_add_u64 v[178:179], v[176:177], 0, s[8:9]
	global_store_dwordx4 v[178:179], v[28:31], off
	s_waitcnt vmcnt(2)
	v_pk_add_f32 v[180:181], v[180:181], v[182:183]
	v_pk_add_f32 v[184:185], v[184:185], v[186:187]
	v_pk_add_f32 v[188:189], v[188:189], v[190:191]
	v_pk_add_f32 v[192:193], v[192:193], v[194:195]
	v_pk_add_f32 v[180:181], v[180:181], v[184:185]
	v_pk_add_f32 v[188:189], v[188:189], v[192:193]
	v_pk_add_f32 v[180:181], v[180:181], v[188:189]
	v_add_f32_e32 v149, v180, v181
	v_fmamk_f32 v149, v149, 0x3a800000, v158
	v_rsq_f32_e32 v150, v149
	v_pk_mul_f32 v[4:5], v[12:13], v[4:5]
	v_pk_mul_f32 v[6:7], v[14:15], v[6:7]
	v_pk_mul_f32 v[0:1], v[8:9], v[0:1]
	v_pk_mul_f32 v[2:3], v[10:11], v[2:3]
	v_mul_f32_e32 v150, 0xbfb8aa3b, v150
	v_mov_b32_e32 v151, v149
	v_pk_mul_f32 v[12:13], v[12:13], v[150:151] op_sel_hi:[1,0]
	v_pk_mul_f32 v[14:15], v[14:15], v[150:151] op_sel_hi:[1,0]
	v_pk_mul_f32 v[8:9], v[8:9], v[150:151] op_sel_hi:[1,0]
	v_pk_mul_f32 v[10:11], v[10:11], v[150:151] op_sel_hi:[1,0]
	v_exp_f32_e32 v12, v12
	v_exp_f32_e32 v13, v13
	v_exp_f32_e32 v14, v14
	v_exp_f32_e32 v15, v15
	v_exp_f32_e32 v8, v8
	v_exp_f32_e32 v9, v9
	v_exp_f32_e32 v10, v10
	v_exp_f32_e32 v11, v11
	v_fma_f32 v12, v12, v149, v149
	v_fma_f32 v13, v13, v149, v149
	v_fma_f32 v14, v14, v149, v149
	v_fma_f32 v15, v15, v149, v149
	v_fma_f32 v8, v8, v149, v149
	v_fma_f32 v9, v9, v149, v149
	v_fma_f32 v10, v10, v149, v149
	v_fma_f32 v11, v11, v149, v149
	v_rcp_f32_e32 v12, v12
	v_rcp_f32_e32 v13, v13
	v_rcp_f32_e32 v14, v14
	v_rcp_f32_e32 v15, v15
	v_rcp_f32_e32 v8, v8
	v_rcp_f32_e32 v9, v9
	v_rcp_f32_e32 v10, v10
	v_rcp_f32_e32 v11, v11
	s_mov_b32 s8, 0xf2000
	v_pk_mul_f32 v[4:5], v[4:5], v[12:13]
	v_pk_mul_f32 v[6:7], v[6:7], v[14:15]
	v_pk_mul_f32 v[0:1], v[0:1], v[8:9]
	v_pk_mul_f32 v[2:3], v[2:3], v[10:11]
	v_cvt_pk_bf16_f32 v12, v4, v5
	v_cvt_pk_bf16_f32 v13, v6, v7
	v_cvt_pk_bf16_f32 v14, v0, v1
	v_cvt_pk_bf16_f32 v15, v2, v3
	v_lshl_add_u64 v[178:179], v[176:177], 0, s[8:9]
	global_store_dwordx4 v[178:179], v[12:15], off
	s_andn2_b64 vcc, exec, s[6:7]
	s_mov_b64 s[6:7], -1
	s_cbranch_vccnz .LBB0_237
	s_andn2_b64 vcc, exec, s[12:13]
	s_cbranch_vccnz .LBB0_236
	s_barrier
	s_branch .LBB0_236

; __device__ __forceinline__ unsigned cvtpk(float lo, float hi) { f32x2_t v = {lo, hi}; bf16x2_t b = __builtin_convertvector(v, bf16x2_t); return __builtin_bit_cast(unsigned, b); }
; __device__ __forceinline__ float ssq_sum(const float* p) {
;     const f32x4 a = *(const f32x4*)p, b = *(const f32x4*)(p + 4), c = *(const f32x4*)(p + 8), d = *(const f32x4*)(p + 12);
;     return (((a[0] + a[1]) + (a[2] + a[3])) + ((b[0] + b[1]) + (b[2] + b[3]))) + (((c[0] + c[1]) + (c[2] + c[3])) + ((d[0] + d[1]) + (d[2] + d[3])));
;     __device__ __forceinline__ void operator()(const f32x4 (&acc)[2][2][4][2], const Unit& u, int wr, int wc, int fr, int fq) const {
;         const int row0 = u.pm * BM + wr * 64 + fr, col0 = u.pn * 128 + wc * 32 + 8 * fq;
; #pragma unroll
;         for (int ai = 0; ai < 2; ++ai)
; #pragma unroll
;             for (int m = 0; m < 4; ++m) {
;                 const int row = row0 + ai * HALF + m * 16;
;                 const float rs = 1.0f / sqrtf(ssq_sum(ssq + (size_t)row * 16) * (1.0f / DM) + EPS);
;                 float hv[8];
; #pragma unroll
;                 for (int n = 0; n < 2; ++n)
; #pragma unroll
;                     for (int e = 0; e < 4; ++e) {
;                         const float gg = acc[ai][0][m][n][e] * rs, uu = acc[ai][1][m][n][e] * rs;
;                         const float den = 1.0f + __builtin_amdgcn_exp2f(-gg * LOG2E);
;                         hv[n * 4 + e] = gg * uu * __builtin_amdgcn_rcpf(den);
;                     }
;                 u32x4 w; w.x = cvtpk(hv[0], hv[1]); w.y = cvtpk(hv[2], hv[3]); w.z = cvtpk(hv[4], hv[5]); w.w = cvtpk(hv[6], hv[7]);
;                 *(u32x4*)(H + (size_t)row * DFF + col0) = w;
;             }
.LBB0_1054:
	v_lshl_add_u32 v148, s8, 8, v152
	v_ashrrev_i32_e32 v149, 31, v148
	v_lshlrev_b64 v[144:145], 6, v[148:149]
	v_lshl_add_u64 v[144:145], s[16:17], 0, v[144:145]
	global_load_dwordx4 v[160:163], v[144:145], off
	global_load_dwordx4 v[164:167], v[144:145], off offset:16
	global_load_dwordx4 v[168:171], v[144:145], off offset:32
	global_load_dwordx4 v[172:175], v[144:145], off offset:48
	v_mov_b64_e32 v[146:147], s[14:15]
	v_mad_i64_i32 v[176:177], s[8:9], v148, s51, v[146:147]
	v_lshl_or_b32 v150, s2, 7, v154
	v_mov_b32_e32 v151, 0
	v_lshlrev_b64 v[150:151], 1, v[150:151]
	v_lshl_add_u64 v[176:177], v[176:177], 0, v[150:151]
	s_mov_b32 s8, 0x2000
	s_mov_b32 s9, 0
	v_lshl_add_u64 v[146:147], v[144:145], 0, s[8:9]
	global_load_dwordx4 v[180:183], v[144:145], off offset:1024
	global_load_dwordx4 v[184:187], v[144:145], off offset:1040
	global_load_dwordx4 v[188:191], v[144:145], off offset:1056
	global_load_dwordx4 v[192:195], v[144:145], off offset:1072
	s_waitcnt vmcnt(4)
	v_pk_add_f32 v[160:161], v[160:161], v[162:163]
	v_pk_add_f32 v[164:165], v[164:165], v[166:167]
	v_pk_add_f32 v[168:169], v[168:169], v[170:171]
	v_pk_add_f32 v[172:173], v[172:173], v[174:175]
	v_pk_add_f32 v[160:161], v[160:161], v[164:165]
	v_pk_add_f32 v[168:169], v[168:169], v[172:173]
	v_pk_add_f32 v[160:161], v[160:161], v[168:169]
	v_add_f32_e32 v149, v160, v161
	v_fmamk_f32 v149, v149, 0x3a800000, v158
	v_rsq_f32_e32 v150, v149
	global_load_dwordx4 v[196:199], v[144:145], off offset:2048
	global_load_dwordx4 v[200:203], v[144:145], off offset:2064
	global_load_dwordx4 v[204:207], v[144:145], off offset:2080
	global_load_dwordx4 v[208:211], v[144:145], off offset:2096
	v_pk_mul_f32 v[116:117], v[124:125], v[116:117]
	v_pk_mul_f32 v[118:119], v[126:127], v[118:119]
	v_pk_mul_f32 v[112:113], v[120:121], v[112:113]
	v_pk_mul_f32 v[114:115], v[122:123], v[114:115]
	v_mul_f32_e32 v150, 0xbfb8aa3b, v150
	v_mov_b32_e32 v151, v149
	v_pk_mul_f32 v[124:125], v[124:125], v[150:151] op_sel_hi:[1,0]
	v_pk_mul_f32 v[126:127], v[126:127], v[150:151] op_sel_hi:[1,0]
	v_pk_mul_f32 v[120:121], v[120:121], v[150:151] op_sel_hi:[1,0]
	v_pk_mul_f32 v[122:123], v[122:123], v[150:151] op_sel_hi:[1,0]
	v_exp_f32_e32 v124, v124
	v_exp_f32_e32 v125, v125
	v_exp_f32_e32 v126, v126
	v_exp_f32_e32 v127, v127
	v_exp_f32_e32 v120, v120
	v_exp_f32_e32 v121, v121
	v_exp_f32_e32 v122, v122
	v_exp_f32_e32 v123, v123
	v_fma_f32 v124, v124, v149, v149
	v_fma_f32 v125, v125, v149, v149
	v_fma_f32 v126, v126, v149, v149
	v_fma_f32 v127, v127, v149, v149
	v_fma_f32 v120, v120, v149, v149
	v_fma_f32 v121, v121, v149, v149
	v_fma_f32 v122, v122, v149, v149
	v_fma_f32 v123, v123, v149, v149
	v_rcp_f32_e32 v124, v124
	v_rcp_f32_e32 v125, v125
	v_rcp_f32_e32 v126, v126
	v_rcp_f32_e32 v127, v127
	v_rcp_f32_e32 v120, v120
	v_rcp_f32_e32 v121, v121
	v_rcp_f32_e32 v122, v122
	v_rcp_f32_e32 v123, v123
	v_pk_mul_f32 v[116:117], v[116:117], v[124:125]
	v_pk_mul_f32 v[118:119], v[118:119], v[126:127]
	v_pk_mul_f32 v[112:113], v[112:113], v[120:121]
	v_pk_mul_f32 v[114:115], v[114:115], v[122:123]
	v_cvt_pk_bf16_f32 v124, v116, v117
	v_cvt_pk_bf16_f32 v125, v118, v119
	v_cvt_pk_bf16_f32 v126, v112, v113
	v_cvt_pk_bf16_f32 v127, v114, v115
	global_store_dwordx4 v[176:177], v[124:127], off
	s_waitcnt vmcnt(5)
	v_pk_add_f32 v[180:181], v[180:181], v[182:183]
	v_pk_add_f32 v[184:185], v[184:185], v[186:187]
	v_pk_add_f32 v[188:189], v[188:189], v[190:191]
	v_pk_add_f32 v[192:193], v[192:193], v[194:195]
	v_pk_add_f32 v[180:181], v[180:181], v[184:185]
	v_pk_add_f32 v[188:189], v[188:189], v[192:193]
	v_pk_add_f32 v[180:181], v[180:181], v[188:189]
	v_add_f32_e32 v149, v180, v181
	v_fmamk_f32 v149, v149, 0x3a800000, v158
	v_rsq_f32_e32 v150, v149
	global_load_dwordx4 v[160:163], v[144:145], off offset:3072
	global_load_dwordx4 v[164:167], v[144:145], off offset:3088
	global_load_dwordx4 v[168:171], v[144:145], off offset:3104
	global_load_dwordx4 v[172:175], v[144:145], off offset:3120
	v_pk_mul_f32 v[100:101], v[108:109], v[100:101]
	v_pk_mul_f32 v[102:103], v[110:111], v[102:103]
	v_pk_mul_f32 v[96:97], v[104:105], v[96:97]
	v_pk_mul_f32 v[98:99], v[106:107], v[98:99]
	v_mul_f32_e32 v150, 0xbfb8aa3b, v150
	v_mov_b32_e32 v151, v149
	v_pk_mul_f32 v[108:109], v[108:109], v[150:151] op_sel_hi:[1,0]
	v_pk_mul_f32 v[110:111], v[110:111], v[150:151] op_sel_hi:[1,0]
	v_pk_mul_f32 v[104:105], v[104:105], v[150:151] op_sel_hi:[1,0]
	v_pk_mul_f32 v[106:107], v[106:107], v[150:151] op_sel_hi:[1,0]
	v_exp_f32_e32 v108, v108
	v_exp_f32_e32 v109, v109
	v_exp_f32_e32 v110, v110
	v_exp_f32_e32 v111, v111
	v_exp_f32_e32 v104, v104
	v_exp_f32_e32 v105, v105
	v_exp_f32_e32 v106, v106
	v_exp_f32_e32 v107, v107
	v_fma_f32 v108, v108, v149, v149
	v_fma_f32 v109, v109, v149, v149
	v_fma_f32 v110, v110, v149, v149
	v_fma_f32 v111, v111, v149, v149
	v_fma_f32 v104, v104, v149, v149
	v_fma_f32 v105, v105, v149, v149
	v_fma_f32 v106, v106, v149, v149
	v_fma_f32 v107, v107, v149, v149
	v_rcp_f32_e32 v108, v108
	v_rcp_f32_e32 v109, v109
	v_rcp_f32_e32 v110, v110
	v_rcp_f32_e32 v111, v111
	v_rcp_f32_e32 v104, v104
	v_rcp_f32_e32 v105, v105
	v_rcp_f32_e32 v106, v106
	v_rcp_f32_e32 v107, v107
	s_mov_b32 s8, 0x16000
	v_pk_mul_f32 v[100:101], v[100:101], v[108:109]
	v_pk_mul_f32 v[102:103], v[102:103], v[110:111]
	v_pk_mul_f32 v[96:97], v[96:97], v[104:105]
	v_pk_mul_f32 v[98:99], v[98:99], v[106:107]
	v_cvt_pk_bf16_f32 v108, v100, v101
	v_cvt_pk_bf16_f32 v109, v102, v103
	v_cvt_pk_bf16_f32 v110, v96, v97
	v_cvt_pk_bf16_f32 v111, v98, v99
	v_lshl_add_u64 v[178:179], v[176:177], 0, s[8:9]
	global_store_dwordx4 v[178:179], v[108:111], off
	s_waitcnt vmcnt(6)
; __device__ __forceinline__ unsigned cvtpk(float lo, float hi) { f32x2_t v = {lo, hi}; bf16x2_t b = __builtin_convertvector(v, bf16x2_t); return __builtin_bit_cast(unsigned, b); }
; __device__ __forceinline__ float ssq_sum(const float* p) {
;     const f32x4 a = *(const f32x4*)p, b = *(const f32x4*)(p + 4), c = *(const f32x4*)(p + 8), d = *(const f32x4*)(p + 12);
;     return (((a[0] + a[1]) + (a[2] + a[3])) + ((b[0] + b[1]) + (b[2] + b[3]))) + (((c[0] + c[1]) + (c[2] + c[3])) + ((d[0] + d[1]) + (d[2] + d[3])));
;     __device__ __forceinline__ void operator()(const f32x4 (&acc)[2][2][4][2], const Unit& u, int wr, int wc, int fr, int fq) const {
;         const int row0 = u.pm * BM + wr * 64 + fr, col0 = u.pn * 128 + wc * 32 + 8 * fq;
; #pragma unroll
;         for (int ai = 0; ai < 2; ++ai)
; #pragma unroll
;             for (int m = 0; m < 4; ++m) {
;                 const int row = row0 + ai * HALF + m * 16;
;                 const float rs = 1.0f / sqrtf(ssq_sum(ssq + (size_t)row * 16) * (1.0f / DM) + EPS);
;                 float hv[8];
; #pragma unroll
;                 for (int n = 0; n < 2; ++n)
; #pragma unroll
;                     for (int e = 0; e < 4; ++e) {
;                         const float gg = acc[ai][0][m][n][e] * rs, uu = acc[ai][1][m][n][e] * rs;
;                         const float den = 1.0f + __builtin_amdgcn_exp2f(-gg * LOG2E);
;                         hv[n * 4 + e] = gg * uu * __builtin_amdgcn_rcpf(den);
;                     }
;                 u32x4 w; w.x = cvtpk(hv[0], hv[1]); w.y = cvtpk(hv[2], hv[3]); w.z = cvtpk(hv[4], hv[5]); w.w = cvtpk(hv[6], hv[7]);
;                 *(u32x4*)(H + (size_t)row * DFF + col0) = w;
;             }
	v_pk_add_f32 v[196:197], v[196:197], v[198:199]
	v_pk_add_f32 v[200:201], v[200:201], v[202:203]
	v_pk_add_f32 v[204:205], v[204:205], v[206:207]
	v_pk_add_f32 v[208:209], v[208:209], v[210:211]
	v_pk_add_f32 v[196:197], v[196:197], v[200:201]
	v_pk_add_f32 v[204:205], v[204:205], v[208:209]
	v_pk_add_f32 v[196:197], v[196:197], v[204:205]
	v_add_f32_e32 v149, v196, v197
	v_fmamk_f32 v149, v149, 0x3a800000, v158
	v_rsq_f32_e32 v150, v149
	global_load_dwordx4 v[180:183], v[146:147], off
	global_load_dwordx4 v[184:187], v[146:147], off offset:16
	global_load_dwordx4 v[188:191], v[146:147], off offset:32
	global_load_dwordx4 v[192:195], v[146:147], off offset:48
	v_pk_mul_f32 v[84:85], v[92:93], v[84:85]
	v_pk_mul_f32 v[86:87], v[94:95], v[86:87]
	v_pk_mul_f32 v[80:81], v[88:89], v[80:81]
	v_pk_mul_f32 v[82:83], v[90:91], v[82:83]
	v_mul_f32_e32 v150, 0xbfb8aa3b, v150
	v_mov_b32_e32 v151, v149
	v_pk_mul_f32 v[92:93], v[92:93], v[150:151] op_sel_hi:[1,0]
	v_pk_mul_f32 v[94:95], v[94:95], v[150:151] op_sel_hi:[1,0]
	v_pk_mul_f32 v[88:89], v[88:89], v[150:151] op_sel_hi:[1,0]
	v_pk_mul_f32 v[90:91], v[90:91], v[150:151] op_sel_hi:[1,0]
	v_exp_f32_e32 v92, v92
	v_exp_f32_e32 v93, v93
	v_exp_f32_e32 v94, v94
	v_exp_f32_e32 v95, v95
	v_exp_f32_e32 v88, v88
	v_exp_f32_e32 v89, v89
	v_exp_f32_e32 v90, v90
	v_exp_f32_e32 v91, v91
	v_fma_f32 v92, v92, v149, v149
	v_fma_f32 v93, v93, v149, v149
	v_fma_f32 v94, v94, v149, v149
	v_fma_f32 v95, v95, v149, v149
	v_fma_f32 v88, v88, v149, v149
	v_fma_f32 v89, v89, v149, v149
	v_fma_f32 v90, v90, v149, v149
	v_fma_f32 v91, v91, v149, v149
	v_rcp_f32_e32 v92, v92
	v_rcp_f32_e32 v93, v93
	v_rcp_f32_e32 v94, v94
	v_rcp_f32_e32 v95, v95
	v_rcp_f32_e32 v88, v88
	v_rcp_f32_e32 v89, v89
	v_rcp_f32_e32 v90, v90
	v_rcp_f32_e32 v91, v91
	s_mov_b32 s8, 0x2c000
	v_pk_mul_f32 v[84:85], v[84:85], v[92:93]
	v_pk_mul_f32 v[86:87], v[86:87], v[94:95]
	v_pk_mul_f32 v[80:81], v[80:81], v[88:89]
	v_pk_mul_f32 v[82:83], v[82:83], v[90:91]
	v_cvt_pk_bf16_f32 v92, v84, v85
	v_cvt_pk_bf16_f32 v93, v86, v87
	v_cvt_pk_bf16_f32 v94, v80, v81
	v_cvt_pk_bf16_f32 v95, v82, v83
	v_lshl_add_u64 v[178:179], v[176:177], 0, s[8:9]
	global_store_dwordx4 v[178:179], v[92:95], off
	s_waitcnt vmcnt(6)
	v_pk_add_f32 v[160:161], v[160:161], v[162:163]
	v_pk_add_f32 v[164:165], v[164:165], v[166:167]
	v_pk_add_f32 v[168:169], v[168:169], v[170:171]
	v_pk_add_f32 v[172:173], v[172:173], v[174:175]
	v_pk_add_f32 v[160:161], v[160:161], v[164:165]
	v_pk_add_f32 v[168:169], v[168:169], v[172:173]
	v_pk_add_f32 v[160:161], v[160:161], v[168:169]
	v_add_f32_e32 v149, v160, v161
	v_fmamk_f32 v149, v149, 0x3a800000, v158
	v_rsq_f32_e32 v150, v149
	global_load_dwordx4 v[196:199], v[146:147], off offset:1024
	global_load_dwordx4 v[200:203], v[146:147], off offset:1040
	global_load_dwordx4 v[204:207], v[146:147], off offset:1056
	global_load_dwordx4 v[208:211], v[146:147], off offset:1072
	v_pk_mul_f32 v[68:69], v[76:77], v[68:69]
	v_pk_mul_f32 v[70:71], v[78:79], v[70:71]
	v_pk_mul_f32 v[64:65], v[72:73], v[64:65]
	v_pk_mul_f32 v[66:67], v[74:75], v[66:67]
	v_mul_f32_e32 v150, 0xbfb8aa3b, v150
	v_mov_b32_e32 v151, v149
	v_pk_mul_f32 v[76:77], v[76:77], v[150:151] op_sel_hi:[1,0]
	v_pk_mul_f32 v[78:79], v[78:79], v[150:151] op_sel_hi:[1,0]
	v_pk_mul_f32 v[72:73], v[72:73], v[150:151] op_sel_hi:[1,0]
	v_pk_mul_f32 v[74:75], v[74:75], v[150:151] op_sel_hi:[1,0]
	v_exp_f32_e32 v76, v76
	v_exp_f32_e32 v77, v77
	v_exp_f32_e32 v78, v78
	v_exp_f32_e32 v79, v79
	v_exp_f32_e32 v72, v72
	v_exp_f32_e32 v73, v73
	v_exp_f32_e32 v74, v74
	v_exp_f32_e32 v75, v75
	v_fma_f32 v76, v76, v149, v149
	v_fma_f32 v77, v77, v149, v149
	v_fma_f32 v78, v78, v149, v149
	v_fma_f32 v79, v79, v149, v149
	v_fma_f32 v72, v72, v149, v149
	v_fma_f32 v73, v73, v149, v149
	v_fma_f32 v74, v74, v149, v149
	v_fma_f32 v75, v75, v149, v149
	v_rcp_f32_e32 v76, v76
	v_rcp_f32_e32 v77, v77
	v_rcp_f32_e32 v78, v78
	v_rcp_f32_e32 v79, v79
	v_rcp_f32_e32 v72, v72
	v_rcp_f32_e32 v73, v73
	v_rcp_f32_e32 v74, v74
	v_rcp_f32_e32 v75, v75
	s_mov_b32 s8, 0x42000
	v_pk_mul_f32 v[68:69], v[68:69], v[76:77]
	v_pk_mul_f32 v[70:71], v[70:71], v[78:79]
	v_pk_mul_f32 v[64:65], v[64:65], v[72:73]
	v_pk_mul_f32 v[66:67], v[66:67], v[74:75]
	v_cvt_pk_bf16_f32 v76, v68, v69
	v_cvt_pk_bf16_f32 v77, v70, v71
	v_cvt_pk_bf16_f32 v78, v64, v65
	v_cvt_pk_bf16_f32 v79, v66, v67
	v_lshl_add_u64 v[178:179], v[176:177], 0, s[8:9]
	global_store_dwordx4 v[178:179], v[76:79], off
	s_waitcnt vmcnt(6)
	v_pk_add_f32 v[180:181], v[180:181], v[182:183]
	v_pk_add_f32 v[184:185], v[184:185], v[186:187]
	v_pk_add_f32 v[188:189], v[188:189], v[190:191]
	v_pk_add_f32 v[192:193], v[192:193], v[194:195]
	v_pk_add_f32 v[180:181], v[180:181], v[184:185]
	v_pk_add_f32 v[188:189], v[188:189], v[192:193]
	v_pk_add_f32 v[180:181], v[180:181], v[188:189]
	v_add_f32_e32 v149, v180, v181
	v_fmamk_f32 v149, v149, 0x3a800000, v158
	v_rsq_f32_e32 v150, v149
	global_load_dwordx4 v[160:163], v[146:147], off offset:2048
	global_load_dwordx4 v[164:167], v[146:147], off offset:2064
	global_load_dwordx4 v[168:171], v[146:147], off offset:2080
	global_load_dwordx4 v[172:175], v[146:147], off offset:2096
	v_pk_mul_f32 v[52:53], v[60:61], v[52:53]
	v_pk_mul_f32 v[54:55], v[62:63], v[54:55]
	v_pk_mul_f32 v[48:49], v[56:57], v[48:49]
	v_pk_mul_f32 v[50:51], v[58:59], v[50:51]
	v_mul_f32_e32 v150, 0xbfb8aa3b, v150
	v_mov_b32_e32 v151, v149
	v_pk_mul_f32 v[60:61], v[60:61], v[150:151] op_sel_hi:[1,0]
	v_pk_mul_f32 v[62:63], v[62:63], v[150:151] op_sel_hi:[1,0]
	v_pk_mul_f32 v[56:57], v[56:57], v[150:151] op_sel_hi:[1,0]
	v_pk_mul_f32 v[58:59], v[58:59], v[150:151] op_sel_hi:[1,0]
	v_exp_f32_e32 v60, v60
	v_exp_f32_e32 v61, v61
	v_exp_f32_e32 v62, v62
	v_exp_f32_e32 v63, v63
	v_exp_f32_e32 v56, v56
	v_exp_f32_e32 v57, v57
	v_exp_f32_e32 v58, v58
	v_exp_f32_e32 v59, v59
	v_fma_f32 v60, v60, v149, v149
	v_fma_f32 v61, v61, v149, v149
	v_fma_f32 v62, v62, v149, v149
	v_fma_f32 v63, v63, v149, v149
	v_fma_f32 v56, v56, v149, v149
	v_fma_f32 v57, v57, v149, v149
	v_fma_f32 v58, v58, v149, v149
	v_fma_f32 v59, v59, v149, v149
	v_rcp_f32_e32 v60, v60
	v_rcp_f32_e32 v61, v61
	v_rcp_f32_e32 v62, v62
	v_rcp_f32_e32 v63, v63
	v_rcp_f32_e32 v56, v56
	v_rcp_f32_e32 v57, v57
	v_rcp_f32_e32 v58, v58
	v_rcp_f32_e32 v59, v59
	s_mov_b32 s8, 0xb0000
	v_pk_mul_f32 v[52:53], v[52:53], v[60:61]
	v_pk_mul_f32 v[54:55], v[54:55], v[62:63]
	v_pk_mul_f32 v[48:49], v[48:49], v[56:57]
	v_pk_mul_f32 v[50:51], v[50:51], v[58:59]
	v_cvt_pk_bf16_f32 v60, v52, v53
	v_cvt_pk_bf16_f32 v61, v54, v55
	v_cvt_pk_bf16_f32 v62, v48, v49
	v_cvt_pk_bf16_f32 v63, v50, v51
	v_lshl_add_u64 v[178:179], v[176:177], 0, s[8:9]
	global_store_dwordx4 v[178:179], v[60:63], off
	s_waitcnt vmcnt(6)
; __device__ __forceinline__ unsigned cvtpk(float lo, float hi) { f32x2_t v = {lo, hi}; bf16x2_t b = __builtin_convertvector(v, bf16x2_t); return __builtin_bit_cast(unsigned, b); }
;     __device__ __forceinline__ void operator()(const f32x4 (&acc)[2][2][4][2], const Unit& u, int wr, int wc, int fr, int fq) const {
;     ...
;                 const int row = row0 + ai * HALF + m * 16;
;                 const float rs = 1.0f / sqrtf(ssq_sum(ssq + (size_t)row * 16) * (1.0f / DM) + EPS);
;                 float hv[8];
; #pragma unroll
;                 for (int n = 0; n < 2; ++n)
; #pragma unroll
;                     for (int e = 0; e < 4; ++e) {
;                         const float gg = acc[ai][0][m][n][e] * rs, uu = acc[ai][1][m][n][e] * rs;
;                         const float den = 1.0f + __builtin_amdgcn_exp2f(-gg * LOG2E);
;                         hv[n * 4 + e] = gg * uu * __builtin_amdgcn_rcpf(den);
;                     }
;                 u32x4 w; w.x = cvtpk(hv[0], hv[1]); w.y = cvtpk(hv[2], hv[3]); w.z = cvtpk(hv[4], hv[5]); w.w = cvtpk(hv[6], hv[7]);
;                 *(u32x4*)(H + (size_t)row * DFF + col0) = w;
	v_pk_add_f32 v[196:197], v[196:197], v[198:199]
	v_pk_add_f32 v[200:201], v[200:201], v[202:203]
	v_pk_add_f32 v[204:205], v[204:205], v[206:207]
	v_pk_add_f32 v[208:209], v[208:209], v[210:211]
	v_pk_add_f32 v[196:197], v[196:197], v[200:201]
	v_pk_add_f32 v[204:205], v[204:205], v[208:209]
	v_pk_add_f32 v[196:197], v[196:197], v[204:205]
	v_add_f32_e32 v149, v196, v197
	v_fmamk_f32 v149, v149, 0x3a800000, v158
	v_rsq_f32_e32 v150, v149
	global_load_dwordx4 v[180:183], v[146:147], off offset:3072
	global_load_dwordx4 v[184:187], v[146:147], off offset:3088
	global_load_dwordx4 v[188:191], v[146:147], off offset:3104
	global_load_dwordx4 v[192:195], v[146:147], off offset:3120
	v_pk_mul_f32 v[36:37], v[44:45], v[36:37]
	v_pk_mul_f32 v[38:39], v[46:47], v[38:39]
	v_pk_mul_f32 v[32:33], v[40:41], v[32:33]
	v_pk_mul_f32 v[34:35], v[42:43], v[34:35]
	v_mul_f32_e32 v150, 0xbfb8aa3b, v150
	v_mov_b32_e32 v151, v149
	v_pk_mul_f32 v[44:45], v[44:45], v[150:151] op_sel_hi:[1,0]
	v_pk_mul_f32 v[46:47], v[46:47], v[150:151] op_sel_hi:[1,0]
	v_pk_mul_f32 v[40:41], v[40:41], v[150:151] op_sel_hi:[1,0]
	v_pk_mul_f32 v[42:43], v[42:43], v[150:151] op_sel_hi:[1,0]
	v_exp_f32_e32 v44, v44
	v_exp_f32_e32 v45, v45
	v_exp_f32_e32 v46, v46
	v_exp_f32_e32 v47, v47
	v_exp_f32_e32 v40, v40
	v_exp_f32_e32 v41, v41
	v_exp_f32_e32 v42, v42
	v_exp_f32_e32 v43, v43
	v_fma_f32 v44, v44, v149, v149
	v_fma_f32 v45, v45, v149, v149
	v_fma_f32 v46, v46, v149, v149
	v_fma_f32 v47, v47, v149, v149
	v_fma_f32 v40, v40, v149, v149
	v_fma_f32 v41, v41, v149, v149
	v_fma_f32 v42, v42, v149, v149
	v_fma_f32 v43, v43, v149, v149
	v_rcp_f32_e32 v44, v44
	v_rcp_f32_e32 v45, v45
	v_rcp_f32_e32 v46, v46
	v_rcp_f32_e32 v47, v47
	v_rcp_f32_e32 v40, v40
	v_rcp_f32_e32 v41, v41
	v_rcp_f32_e32 v42, v42
	v_rcp_f32_e32 v43, v43
	s_mov_b32 s8, 0xc6000
	v_pk_mul_f32 v[36:37], v[36:37], v[44:45]
	v_pk_mul_f32 v[38:39], v[38:39], v[46:47]
	v_pk_mul_f32 v[32:33], v[32:33], v[40:41]
	v_pk_mul_f32 v[34:35], v[34:35], v[42:43]
	v_cvt_pk_bf16_f32 v44, v36, v37
	v_cvt_pk_bf16_f32 v45, v38, v39
	v_cvt_pk_bf16_f32 v46, v32, v33
	v_cvt_pk_bf16_f32 v47, v34, v35
	v_lshl_add_u64 v[178:179], v[176:177], 0, s[8:9]
	global_store_dwordx4 v[178:179], v[44:47], off
	s_waitcnt vmcnt(6)
	v_pk_add_f32 v[160:161], v[160:161], v[162:163]
	v_pk_add_f32 v[164:165], v[164:165], v[166:167]
	v_pk_add_f32 v[168:169], v[168:169], v[170:171]
	v_pk_add_f32 v[172:173], v[172:173], v[174:175]
	v_pk_add_f32 v[160:161], v[160:161], v[164:165]
	v_pk_add_f32 v[168:169], v[168:169], v[172:173]
	v_pk_add_f32 v[160:161], v[160:161], v[168:169]
	v_add_f32_e32 v149, v160, v161
	v_fmamk_f32 v149, v149, 0x3a800000, v158
	v_rsq_f32_e32 v150, v149
	v_pk_mul_f32 v[20:21], v[28:29], v[20:21]
	v_pk_mul_f32 v[22:23], v[30:31], v[22:23]
	v_pk_mul_f32 v[16:17], v[24:25], v[16:17]
	v_pk_mul_f32 v[18:19], v[26:27], v[18:19]
	v_mul_f32_e32 v150, 0xbfb8aa3b, v150
	v_mov_b32_e32 v151, v149
	v_pk_mul_f32 v[28:29], v[28:29], v[150:151] op_sel_hi:[1,0]
	v_pk_mul_f32 v[30:31], v[30:31], v[150:151] op_sel_hi:[1,0]
	v_pk_mul_f32 v[24:25], v[24:25], v[150:151] op_sel_hi:[1,0]
	v_pk_mul_f32 v[26:27], v[26:27], v[150:151] op_sel_hi:[1,0]
	v_exp_f32_e32 v28, v28
	v_exp_f32_e32 v29, v29
	v_exp_f32_e32 v30, v30
	v_exp_f32_e32 v31, v31
	v_exp_f32_e32 v24, v24
	v_exp_f32_e32 v25, v25
	v_exp_f32_e32 v26, v26
	v_exp_f32_e32 v27, v27
	v_fma_f32 v28, v28, v149, v149
	v_fma_f32 v29, v29, v149, v149
	v_fma_f32 v30, v30, v149, v149
	v_fma_f32 v31, v31, v149, v149
	v_fma_f32 v24, v24, v149, v149
	v_fma_f32 v25, v25, v149, v149
	v_fma_f32 v26, v26, v149, v149
	v_fma_f32 v27, v27, v149, v149
	v_rcp_f32_e32 v28, v28
	v_rcp_f32_e32 v29, v29
	v_rcp_f32_e32 v30, v30
	v_rcp_f32_e32 v31, v31
	v_rcp_f32_e32 v24, v24
	v_rcp_f32_e32 v25, v25
	v_rcp_f32_e32 v26, v26
	v_rcp_f32_e32 v27, v27
	s_mov_b32 s8, 0xdc000
	v_pk_mul_f32 v[20:21], v[20:21], v[28:29]
	v_pk_mul_f32 v[22:23], v[22:23], v[30:31]
	v_pk_mul_f32 v[16:17], v[16:17], v[24:25]
	v_pk_mul_f32 v[18:19], v[18:19], v[26:27]
	v_cvt_pk_bf16_f32 v28, v20, v21
	v_cvt_pk_bf16_f32 v29, v22, v23
	v_cvt_pk_bf16_f32 v30, v16, v17
	v_cvt_pk_bf16_f32 v31, v18, v19
	v_lshl_add_u64 v[178:179], v[176:177], 0, s[8:9]
	global_store_dwordx4 v[178:179], v[28:31], off
	s_waitcnt vmcnt(2)
	v_pk_add_f32 v[180:181], v[180:181], v[182:183]
	v_pk_add_f32 v[184:185], v[184:185], v[186:187]
	v_pk_add_f32 v[188:189], v[188:189], v[190:191]
	v_pk_add_f32 v[192:193], v[192:193], v[194:195]
	v_pk_add_f32 v[180:181], v[180:181], v[184:185]
	v_pk_add_f32 v[188:189], v[188:189], v[192:193]
	v_pk_add_f32 v[180:181], v[180:181], v[188:189]
	v_add_f32_e32 v149, v180, v181
	v_fmamk_f32 v149, v149, 0x3a800000, v158
	v_rsq_f32_e32 v150, v149
	v_pk_mul_f32 v[4:5], v[12:13], v[4:5]
	v_pk_mul_f32 v[6:7], v[14:15], v[6:7]
	v_pk_mul_f32 v[0:1], v[8:9], v[0:1]
	v_pk_mul_f32 v[2:3], v[10:11], v[2:3]
	v_mul_f32_e32 v150, 0xbfb8aa3b, v150
	v_mov_b32_e32 v151, v149
	v_pk_mul_f32 v[12:13], v[12:13], v[150:151] op_sel_hi:[1,0]
	v_pk_mul_f32 v[14:15], v[14:15], v[150:151] op_sel_hi:[1,0]
	v_pk_mul_f32 v[8:9], v[8:9], v[150:151] op_sel_hi:[1,0]
	v_pk_mul_f32 v[10:11], v[10:11], v[150:151] op_sel_hi:[1,0]
	v_exp_f32_e32 v12, v12
	v_exp_f32_e32 v13, v13
	v_exp_f32_e32 v14, v14
	v_exp_f32_e32 v15, v15
	v_exp_f32_e32 v8, v8
	v_exp_f32_e32 v9, v9
	v_exp_f32_e32 v10, v10
	v_exp_f32_e32 v11, v11
	v_fma_f32 v12, v12, v149, v149
	v_fma_f32 v13, v13, v149, v149
	v_fma_f32 v14, v14, v149, v149
	v_fma_f32 v15, v15, v149, v149
	v_fma_f32 v8, v8, v149, v149
	v_fma_f32 v9, v9, v149, v149
	v_fma_f32 v10, v10, v149, v149
	v_fma_f32 v11, v11, v149, v149
	v_rcp_f32_e32 v12, v12
	v_rcp_f32_e32 v13, v13
	v_rcp_f32_e32 v14, v14
	v_rcp_f32_e32 v15, v15
	v_rcp_f32_e32 v8, v8
	v_rcp_f32_e32 v9, v9
	v_rcp_f32_e32 v10, v10
	v_rcp_f32_e32 v11, v11
	s_mov_b32 s8, 0xf2000
	v_pk_mul_f32 v[4:5], v[4:5], v[12:13]
	v_pk_mul_f32 v[6:7], v[6:7], v[14:15]
	v_pk_mul_f32 v[0:1], v[0:1], v[8:9]
	v_pk_mul_f32 v[2:3], v[2:3], v[10:11]
	v_cvt_pk_bf16_f32 v12, v4, v5
	v_cvt_pk_bf16_f32 v13, v6, v7
	v_cvt_pk_bf16_f32 v14, v0, v1
	v_cvt_pk_bf16_f32 v15, v2, v3
	v_lshl_add_u64 v[178:179], v[176:177], 0, s[8:9]
	global_store_dwordx4 v[178:179], v[12:15], off
	s_andn2_b64 vcc, exec, s[6:7]
	s_mov_b64 s[6:7], -1
	s_cbranch_vccnz .LBB0_1047
	s_andn2_b64 vcc, exec, s[12:13]
	s_cbranch_vccnz .LBB0_1046
	s_barrier
	s_branch .LBB0_1046
